# v025c: single-item SGU copy MFMA loop pipelined like the 3-item copy; sample item: second staging loads of stages B and C issued with the first; 3-item SGU loop: W fragments, b_s and c_u rows issued a
# baseline (speedup 1.0000x reference)
.LBB0_121:
	v_readlane_b32 s0, v253, 43
	v_readlane_b32 s1, v253, 44
	s_or_b32 s0, s0, s12
	s_lshl_b64 s[0:1], s[0:1], 9
	v_readlane_b32 s16, v252, 40
	v_readlane_b32 s17, v252, 41
	s_add_u32 s0, s16, s0
	v_lshl_or_b32 v36, v183, 2, s10
	s_addc_u32 s1, s17, s1
	v_ashrrev_i32_e32 v37, 31, v36
	v_lshl_add_u64 v[32:33], v[36:37], 2, s[0:1]
	v_lshlrev_b32_e32 v38, 2, v34
	v_mul_lo_u32 v36, v36, s66
	v_add3_u32 v36, 0, v38, v36
	v_add_u32_e32 v37, 0x9000, v36
	s_lshl_b32 s82, s12, 8
	v_lshlrev_b32_e32 v192, 1, v182
	s_mov_b64 s[0:1], s[42:43]
	v_readlane_b32 s18, v252, 42
	v_readlane_b32 s19, v252, 43
	v_readlane_b32 s20, v252, 44
	v_readlane_b32 s21, v252, 45
	v_readlane_b32 s22, v252, 46
	v_readlane_b32 s23, v252, 47
	v_readlane_b32 s24, v252, 48
	v_readlane_b32 s25, v252, 49
	v_readlane_b32 s26, v252, 50
	v_readlane_b32 s27, v252, 51
	v_readlane_b32 s28, v252, 52
	v_readlane_b32 s29, v252, 53
	v_readlane_b32 s30, v252, 54
	v_readlane_b32 s31, v252, 55
	s_waitcnt vmcnt(0)
	v_mov_b32_e32 v32, v40
	v_mov_b32_e32 v33, v41
	v_mov_b32_e32 v34, v42
	v_mov_b32_e32 v35, v43
	v_add_f32_e32 v4, v4, v32
	v_add_f32_e32 v0, v0, v32
	ds_write2_b32 v37, v4, v0 offset0:96 offset1:112
	v_add_f32_e32 v0, v25, v33
	v_add_f32_e32 v4, v29, v33
	ds_write2_b32 v37, v0, v4 offset0:132 offset1:148
	v_add_f32_e32 v0, v21, v33
	v_add_f32_e32 v4, v17, v33
	ds_write2_b32 v37, v0, v4 offset0:164 offset1:180
	v_add_f32_e32 v0, v13, v33
	v_add_f32_e32 v4, v9, v33
	ds_write2_b32 v37, v0, v4 offset0:196 offset1:212
	v_add_f32_e32 v0, v5, v33
	v_add_f32_e32 v1, v1, v33
	ds_write2_b32 v37, v0, v1 offset0:228 offset1:244
	v_add_f32_e32 v0, v26, v34
	v_add_f32_e32 v1, v30, v34
	v_add_u32_e32 v4, 0x9400, v36
	ds_write2_b32 v4, v0, v1 offset0:8 offset1:24
	v_add_f32_e32 v0, v22, v34
	v_add_f32_e32 v1, v18, v34
	ds_write2_b32 v4, v0, v1 offset0:40 offset1:56
	v_add_f32_e32 v0, v14, v34
	v_add_f32_e32 v1, v10, v34
	ds_write2_b32 v4, v0, v1 offset0:72 offset1:88
	v_add_f32_e32 v0, v6, v34
	v_add_f32_e32 v1, v2, v34
	ds_write2_b32 v4, v0, v1 offset0:104 offset1:120
	v_add_f32_e32 v0, v27, v35
	v_add_f32_e32 v1, v31, v35
	ds_write2_b32 v4, v0, v1 offset0:140 offset1:156
	v_add_f32_e32 v0, v23, v35
	v_add_f32_e32 v1, v19, v35
	ds_write2_b32 v4, v0, v1 offset0:172 offset1:188
	v_add_f32_e32 v0, v15, v35
	v_add_f32_e32 v1, v11, v35
	ds_write2_b32 v4, v0, v1 offset0:204 offset1:220
	v_add_f32_e32 v0, v7, v35
	v_add_f32_e32 v1, v3, v35
	v_ashrrev_i32_e32 v9, 4, v65
	ds_write2_b32 v4, v0, v1 offset0:236 offset1:252
	v_add_u32_e32 v10, s9, v9
	v_mov_b64_e32 v[0:1], s[4:5]
	v_mad_i64_i32 v[2:3], s[4:5], v10, s76, v[0:1]
	v_lshl_add_u64 v[2:3], v[2:3], 0, s[82:83]
	v_add_f32_e32 v24, v24, v32
	v_add_f32_e32 v28, v28, v32
	v_add_f32_e32 v20, v20, v32
	v_add_f32_e32 v16, v16, v32
	v_add_f32_e32 v12, v12, v32
	v_add_f32_e32 v8, v8, v32
	v_lshl_add_u64 v[2:3], v[2:3], 0, v[192:193]
	ds_write2_b32 v37, v24, v28 offset1:16
	ds_write2_b32 v37, v20, v16 offset0:32 offset1:48
	ds_write2_b32 v37, v12, v8 offset0:64 offset1:80
	s_waitcnt lgkmcnt(0)
	s_barrier
	v_mov_b32_e32 v18, v44
	v_mov_b32_e32 v19, v45
	v_mov_b32_e32 v20, v46
	v_mov_b32_e32 v21, v47
	v_add_u32_e32 v2, 0x200, v65
	v_ashrrev_i32_e32 v38, 4, v2
	v_add_u32_e32 v34, s9, v38
	v_mad_i64_i32 v[2:3], s[4:5], v34, s76, v[0:1]
	v_lshl_add_u64 v[2:3], v[2:3], 0, s[82:83]
	v_lshl_add_u64 v[2:3], v[2:3], 0, v[192:193]
	v_mov_b32_e32 v22, v48
	v_mov_b32_e32 v23, v49
	v_mov_b32_e32 v24, v50
	v_mov_b32_e32 v25, v51
	v_add_u32_e32 v2, 0x400, v65
	v_ashrrev_i32_e32 v39, 4, v2
	v_add_u32_e32 v16, s9, v39
	v_mad_i64_i32 v[2:3], s[4:5], v16, s76, v[0:1]
	v_lshl_add_u64 v[2:3], v[2:3], 0, s[82:83]
	v_lshl_add_u64 v[2:3], v[2:3], 0, v[192:193]
	v_mov_b32_e32 v4, v52
	v_mov_b32_e32 v5, v53
	v_mov_b32_e32 v6, v54
	v_mov_b32_e32 v7, v55
	v_add_u32_e32 v2, 0x600, v65
	v_ashrrev_i32_e32 v40, 4, v2
	v_add_u32_e32 v12, s9, v40
	v_mad_i64_i32 v[0:1], s[4:5], v12, s76, v[0:1]
	v_lshl_add_u64 v[0:1], v[0:1], 0, s[82:83]
	v_lshl_add_u64 v[0:1], v[0:1], 0, v[192:193]
	v_mov_b32_e32 v0, v56
	v_mov_b32_e32 v1, v57
	v_mov_b32_e32 v2, v58
	v_mov_b32_e32 v3, v59
	s_add_u32 s0, s0, s82
	s_addc_u32 s1, s1, 0
	v_lshl_add_u32 v8, v182, 2, 0
	v_lshl_add_u64 v[14:15], s[0:1], 0, v[192:193]
	s_mov_b64 s[0:1], 0x14000800
	v_lshl_add_u64 v[14:15], v[14:15], 0, s[0:1]
	v_mad_u64_u32 v[30:31], s[0:1], v9, s66, v[8:9]
	ds_read_b128 v[26:29], v30 offset:36864
	ds_read_b128 v[30:33], v30 offset:36880
	v_ashrrev_i32_e32 v11, 31, v10
	v_lshlrev_b64 v[10:11], 12, v[10:11]
	v_lshl_add_u64 v[10:11], v[14:15], 0, v[10:11]
	v_ashrrev_i32_e32 v35, 31, v34
	v_ashrrev_i32_e32 v17, 31, v16
	s_add_i32 s8, s8, 1
	v_ashrrev_i32_e32 v13, 31, v12
	s_add_u32 s2, s2, 0x8000
	s_addc_u32 s3, s3, 0
	s_cmp_eq_u32 s8, 3
	s_waitcnt vmcnt(0) lgkmcnt(0)
	v_lshlrev_b32_e32 v36, 16, v18
	v_and_b32_e32 v37, 0xffff0000, v18
	v_pk_mul_f32 v[26:27], v[26:27], v[36:37]
	s_nop 0
	v_cvt_pk_bf16_f32 v18, v26, v27
	v_lshlrev_b32_e32 v26, 16, v19
	v_and_b32_e32 v27, 0xffff0000, v19
	v_pk_mul_f32 v[26:27], v[28:29], v[26:27]
	s_nop 0
	v_cvt_pk_bf16_f32 v19, v26, v27
	v_lshlrev_b32_e32 v26, 16, v20
	v_and_b32_e32 v27, 0xffff0000, v20
	v_pk_mul_f32 v[26:27], v[30:31], v[26:27]
	s_nop 0
	v_cvt_pk_bf16_f32 v20, v26, v27
	v_lshlrev_b32_e32 v26, 16, v21
	v_and_b32_e32 v27, 0xffff0000, v21
	v_pk_mul_f32 v[26:27], v[32:33], v[26:27]
	s_nop 0
	v_cvt_pk_bf16_f32 v21, v26, v27
	global_store_dwordx4 v[10:11], v[18:21], off
	v_mad_u64_u32 v[10:11], s[0:1], v38, s66, v[8:9]
	ds_read_b128 v[18:21], v10 offset:36864
	ds_read_b128 v[26:29], v10 offset:36880
	v_lshlrev_b32_e32 v10, 16, v22
	v_and_b32_e32 v11, 0xffff0000, v22
	s_waitcnt lgkmcnt(0)
	v_pk_mul_f32 v[10:11], v[18:19], v[10:11]
	s_nop 0
	v_cvt_pk_bf16_f32 v18, v10, v11
	v_lshlrev_b32_e32 v10, 16, v23
	v_and_b32_e32 v11, 0xffff0000, v23
	v_pk_mul_f32 v[10:11], v[20:21], v[10:11]
	s_nop 0
	v_cvt_pk_bf16_f32 v19, v10, v11
	v_lshlrev_b32_e32 v10, 16, v24
	v_and_b32_e32 v11, 0xffff0000, v24
	v_pk_mul_f32 v[10:11], v[26:27], v[10:11]
	s_nop 0
	v_cvt_pk_bf16_f32 v20, v10, v11
	v_lshlrev_b32_e32 v10, 16, v25
	v_and_b32_e32 v11, 0xffff0000, v25
	v_pk_mul_f32 v[10:11], v[28:29], v[10:11]
	s_nop 0
	v_cvt_pk_bf16_f32 v21, v10, v11
	v_lshlrev_b64 v[10:11], 12, v[34:35]
	v_lshl_add_u64 v[10:11], v[14:15], 0, v[10:11]
	global_store_dwordx4 v[10:11], v[18:21], off
	v_mad_u64_u32 v[10:11], s[0:1], v39, s66, v[8:9]
	ds_read_b128 v[18:21], v10 offset:36864
	ds_read_b128 v[22:25], v10 offset:36880
	v_lshlrev_b32_e32 v10, 16, v4
	v_and_b32_e32 v11, 0xffff0000, v4
	s_waitcnt lgkmcnt(0)
	v_pk_mul_f32 v[10:11], v[18:19], v[10:11]
	s_nop 0
	v_cvt_pk_bf16_f32 v4, v10, v11
	v_lshlrev_b32_e32 v10, 16, v5
	v_and_b32_e32 v11, 0xffff0000, v5
	v_pk_mul_f32 v[10:11], v[20:21], v[10:11]
	s_nop 0
	v_cvt_pk_bf16_f32 v5, v10, v11
	v_lshlrev_b32_e32 v10, 16, v6
	v_and_b32_e32 v11, 0xffff0000, v6
	v_pk_mul_f32 v[10:11], v[22:23], v[10:11]
	s_nop 0
	v_cvt_pk_bf16_f32 v6, v10, v11
	v_lshlrev_b32_e32 v10, 16, v7
	v_and_b32_e32 v11, 0xffff0000, v7
	v_pk_mul_f32 v[10:11], v[24:25], v[10:11]
	s_nop 0
	v_cvt_pk_bf16_f32 v7, v10, v11
	v_lshlrev_b64 v[10:11], 12, v[16:17]
	v_lshl_add_u64 v[10:11], v[14:15], 0, v[10:11]
	global_store_dwordx4 v[10:11], v[4:7], off
	v_lshlrev_b32_e32 v16, 16, v0
	v_and_b32_e32 v17, 0xffff0000, v0
	v_mad_u64_u32 v[4:5], s[0:1], v40, s66, v[8:9]
	ds_read_b128 v[8:11], v4 offset:36864
	ds_read_b128 v[4:7], v4 offset:36880
	s_waitcnt lgkmcnt(0)
	v_pk_mul_f32 v[8:9], v[8:9], v[16:17]
	s_nop 0
	v_cvt_pk_bf16_f32 v0, v8, v9
	v_lshlrev_b32_e32 v8, 16, v1
	v_and_b32_e32 v9, 0xffff0000, v1
	v_pk_mul_f32 v[8:9], v[10:11], v[8:9]
	s_nop 0
	v_cvt_pk_bf16_f32 v1, v8, v9
	v_lshlrev_b32_e32 v8, 16, v2
	v_and_b32_e32 v9, 0xffff0000, v2
	v_pk_mul_f32 v[4:5], v[4:5], v[8:9]
	s_nop 0
	v_cvt_pk_bf16_f32 v2, v4, v5
	v_lshlrev_b32_e32 v4, 16, v3
	v_and_b32_e32 v5, 0xffff0000, v3
	v_pk_mul_f32 v[4:5], v[6:7], v[4:5]
	s_nop 0
	v_cvt_pk_bf16_f32 v3, v4, v5
	v_lshlrev_b64 v[4:5], 12, v[12:13]
	v_lshl_add_u64 v[4:5], v[14:15], 0, v[4:5]
	global_store_dwordx4 v[4:5], v[0:3], off
	s_waitcnt lgkmcnt(0)
	s_barrier
	s_cbranch_scc1 .LBB0_129

.LBB0_126:
	s_or_b64 exec, exec, s[0:1]
	s_ashr_i32 s11, s11, 7
	s_waitcnt lgkmcnt(3)
	v_mov_b32_e32 v27, 0
	v_and_b32_e32 v34, 15, v65
	s_mov_b64 s[0:1], s[42:43]
	v_add_u32_e32 v60, s10, v34
	v_ashrrev_i32_e32 v61, 31, v60
	v_lshlrev_b64 v[60:61], 8, v[60:61]
	v_lshl_add_u64 v[60:61], s[2:3], 0, v[60:61]
	v_and_b32_e32 v62, 48, v65
	v_mov_b32_e32 v63, 0
	v_lshl_add_u64 v[60:61], v[60:61], 0, v[62:63]
	v_lshl_add_u64 v[60:61], s[0:1], 0, v[60:61]
	global_load_dwordx4 v[104:107], v[60:61], off
	global_load_dwordx4 v[108:111], v[60:61], off offset:64
	global_load_dwordx4 v[112:115], v[60:61], off offset:128
	global_load_dwordx4 v[116:119], v[60:61], off offset:192
	s_lshl_b32 s16, s12, 8
	s_mov_b32 s17, 0
	s_mov_b32 s18, 0x70000
	s_mov_b32 s19, 0
	v_ashrrev_i32_e32 v40, 4, v65
	v_add_u32_e32 v40, s9, v40
	v_mov_b64_e32 v[62:63], s[4:5]
	v_mad_i64_i32 v[60:61], s[20:21], v40, s76, v[62:63]
	v_lshl_add_u64 v[60:61], v[60:61], 0, s[16:17]
	v_lshlrev_b32_e32 v62, 1, v182
	v_mov_b32_e32 v63, 0
	v_lshl_add_u64 v[60:61], v[60:61], 0, v[62:63]
	global_load_dwordx4 v[44:47], v[60:61], off offset:3072
	v_lshl_add_u64 v[60:61], v[60:61], 0, s[18:19]
	global_load_dwordx4 v[48:51], v[60:61], off offset:3072
	v_lshl_add_u64 v[60:61], v[60:61], 0, s[18:19]
	global_load_dwordx4 v[52:55], v[60:61], off offset:3072
	v_lshl_add_u64 v[60:61], v[60:61], 0, s[18:19]
	global_load_dwordx4 v[56:59], v[60:61], off offset:3072
	v_readlane_b32 s20, v253, 43
	v_readlane_b32 s21, v253, 44
	s_or_b32 s20, s20, s12
	s_lshl_b64 s[20:21], s[20:21], 9
	v_readlane_b32 s22, v252, 40
	v_readlane_b32 s23, v252, 41
	s_add_u32 s20, s22, s20
	s_addc_u32 s21, s23, s21
	v_lshl_or_b32 v60, v183, 2, s10
	v_ashrrev_i32_e32 v61, 31, v60
	v_lshl_add_u64 v[60:61], v[60:61], 2, s[20:21]
	global_load_dwordx4 v[40:43], v[60:61], off
	s_cmp_lt_i32 s11, 0
	v_mov_b32_e32 v26, v27
	v_mov_b32_e32 v25, v27
	v_mov_b32_e32 v24, v27
	s_waitcnt lgkmcnt(2)
	v_mov_b32_e32 v31, v27
	v_mov_b32_e32 v30, v27
	v_mov_b32_e32 v29, v27
	v_mov_b32_e32 v28, v27
	v_mov_b32_e32 v23, v27
	v_mov_b32_e32 v22, v27
	v_mov_b32_e32 v21, v27
	v_mov_b32_e32 v20, v27
	v_mov_b32_e32 v19, v27
	v_mov_b32_e32 v18, v27
	v_mov_b32_e32 v17, v27
	v_mov_b32_e32 v16, v27
	s_waitcnt lgkmcnt(0)
	v_mov_b32_e32 v15, v27
	v_mov_b32_e32 v14, v27
	v_mov_b32_e32 v13, v27
	v_mov_b32_e32 v12, v27
	v_mov_b32_e32 v11, v27
	v_mov_b32_e32 v10, v27
	v_mov_b32_e32 v9, v27
	v_mov_b32_e32 v8, v27
	v_mov_b32_e32 v7, v27
	v_mov_b32_e32 v6, v27
	v_mov_b32_e32 v5, v27
	v_mov_b32_e32 v4, v27
	v_mov_b32_e32 v3, v27
	v_mov_b32_e32 v2, v27
	v_mov_b32_e32 v1, v27
	v_mov_b32_e32 v0, v27
	s_barrier
	s_cbranch_scc1 .LBB0_121
	v_lshlrev_b32_e32 v0, 4, v183
	v_mul_u32_u24_e32 v1, 0x110, v34
	v_add3_u32 v35, 0, v0, v1
	v_add_u32_e32 v0, s10, v34
	v_ashrrev_i32_e32 v1, 31, v0
	v_lshlrev_b64 v[0:1], 8, v[0:1]
	v_lshl_add_u64 v[0:1], s[2:3], 0, v[0:1]
	v_and_b32_e32 v192, 48, v65
	v_lshl_add_u64 v[0:1], v[0:1], 0, v[192:193]
	v_lshl_add_u64 v[32:33], s[0:1], 0, v[0:1]
	v_mov_b32_e32 v0, 0
	s_add_i32 s11, s11, 1
	v_mov_b32_e32 v1, v0
	v_mov_b32_e32 v2, v0
	v_mov_b32_e32 v3, v0
	v_mov_b32_e32 v4, v0
	v_mov_b32_e32 v5, v0
	v_mov_b32_e32 v6, v0
	v_mov_b32_e32 v7, v0
	v_mov_b32_e32 v8, v0
	v_mov_b32_e32 v9, v0
	v_mov_b32_e32 v10, v0
	v_mov_b32_e32 v11, v0
	v_mov_b32_e32 v12, v0
	v_mov_b32_e32 v13, v0
	v_mov_b32_e32 v14, v0
	v_mov_b32_e32 v15, v0
	v_mov_b32_e32 v16, v0
	v_mov_b32_e32 v17, v0
	v_mov_b32_e32 v18, v0
	v_mov_b32_e32 v19, v0
	v_mov_b32_e32 v20, v0
	v_mov_b32_e32 v21, v0
	v_mov_b32_e32 v22, v0
	v_mov_b32_e32 v23, v0
	v_mov_b32_e32 v28, v0
	v_mov_b32_e32 v29, v0
	v_mov_b32_e32 v30, v0
	v_mov_b32_e32 v31, v0
	v_mov_b32_e32 v24, v0
	v_mov_b32_e32 v25, v0
	v_mov_b32_e32 v26, v0
	v_mov_b32_e32 v27, v0
.LBB0_128:
	ds_read_b128 v[120:123], v35
	ds_read_b128 v[124:127], v35 offset:4352
	ds_read_b128 v[128:131], v35 offset:8704
	ds_read_b128 v[132:135], v35 offset:13056
	ds_read_b128 v[136:139], v35 offset:17408
	ds_read_b128 v[140:143], v35 offset:21760
	ds_read_b128 v[144:147], v35 offset:26112
	ds_read_b128 v[148:151], v35 offset:30464
	s_cmp_lt_u32 s11, 2
	s_cbranch_scc1 .Lsgu_b_k0
	ds_read_b128 v[152:155], v35 offset:64
	ds_read_b128 v[156:159], v35 offset:4416
	ds_read_b128 v[160:163], v35 offset:8768
	ds_read_b128 v[84:87], v35 offset:13120
	ds_read_b128 v[88:91], v35 offset:17472
	ds_read_b128 v[92:95], v35 offset:21824
	ds_read_b128 v[172:175], v35 offset:26176
	ds_read_b128 v[176:179], v35 offset:30528
	s_waitcnt vmcnt(8)
	s_waitcnt lgkmcnt(8)
	v_mfma_f32_16x16x32_bf16 v[24:27], v[104:107], v[120:123], v[24:27]
	v_mfma_f32_16x16x32_bf16 v[28:31], v[104:107], v[124:127], v[28:31]
	v_mfma_f32_16x16x32_bf16 v[20:23], v[104:107], v[128:131], v[20:23]
	v_mfma_f32_16x16x32_bf16 v[16:19], v[104:107], v[132:135], v[16:19]
	v_mfma_f32_16x16x32_bf16 v[12:15], v[104:107], v[136:139], v[12:15]
	v_mfma_f32_16x16x32_bf16 v[8:11], v[104:107], v[140:143], v[8:11]
	v_mfma_f32_16x16x32_bf16 v[4:7], v[104:107], v[144:147], v[4:7]
	v_mfma_f32_16x16x32_bf16 v[0:3], v[104:107], v[148:151], v[0:3]
	s_cmp_lt_u32 s11, 3
	s_cbranch_scc1 .Lsgu_b_k1
	ds_read_b128 v[120:123], v35 offset:128
	ds_read_b128 v[124:127], v35 offset:4480
	ds_read_b128 v[128:131], v35 offset:8832
	ds_read_b128 v[132:135], v35 offset:13184
	ds_read_b128 v[136:139], v35 offset:17536
	ds_read_b128 v[140:143], v35 offset:21888
	ds_read_b128 v[144:147], v35 offset:26240
	ds_read_b128 v[148:151], v35 offset:30592
	s_waitcnt vmcnt(7)
	s_waitcnt lgkmcnt(8)
	v_mfma_f32_16x16x32_bf16 v[24:27], v[108:111], v[152:155], v[24:27]
	v_mfma_f32_16x16x32_bf16 v[28:31], v[108:111], v[156:159], v[28:31]
	v_mfma_f32_16x16x32_bf16 v[20:23], v[108:111], v[160:163], v[20:23]
	v_mfma_f32_16x16x32_bf16 v[16:19], v[108:111], v[84:87], v[16:19]
	v_mfma_f32_16x16x32_bf16 v[12:15], v[108:111], v[88:91], v[12:15]
	v_mfma_f32_16x16x32_bf16 v[8:11], v[108:111], v[92:95], v[8:11]
	v_mfma_f32_16x16x32_bf16 v[4:7], v[108:111], v[172:175], v[4:7]
	v_mfma_f32_16x16x32_bf16 v[0:3], v[108:111], v[176:179], v[0:3]
	s_cmp_lt_u32 s11, 4
	s_cbranch_scc1 .Lsgu_b_k2
	ds_read_b128 v[152:155], v35 offset:192
	ds_read_b128 v[156:159], v35 offset:4544
	ds_read_b128 v[160:163], v35 offset:8896
	ds_read_b128 v[84:87], v35 offset:13248
	ds_read_b128 v[88:91], v35 offset:17600
	ds_read_b128 v[92:95], v35 offset:21952
	ds_read_b128 v[172:175], v35 offset:26304
	ds_read_b128 v[176:179], v35 offset:30656
	s_waitcnt vmcnt(6)
	s_waitcnt lgkmcnt(8)
	v_mfma_f32_16x16x32_bf16 v[24:27], v[112:115], v[120:123], v[24:27]
	v_mfma_f32_16x16x32_bf16 v[28:31], v[112:115], v[124:127], v[28:31]
	v_mfma_f32_16x16x32_bf16 v[20:23], v[112:115], v[128:131], v[20:23]
	v_mfma_f32_16x16x32_bf16 v[16:19], v[112:115], v[132:135], v[16:19]
	v_mfma_f32_16x16x32_bf16 v[12:15], v[112:115], v[136:139], v[12:15]
	v_mfma_f32_16x16x32_bf16 v[8:11], v[112:115], v[140:143], v[8:11]
	v_mfma_f32_16x16x32_bf16 v[4:7], v[112:115], v[144:147], v[4:7]
	v_mfma_f32_16x16x32_bf16 v[0:3], v[112:115], v[148:151], v[0:3]
	s_waitcnt vmcnt(5)
	s_waitcnt lgkmcnt(0)
	v_mfma_f32_16x16x32_bf16 v[24:27], v[116:119], v[152:155], v[24:27]
	v_mfma_f32_16x16x32_bf16 v[28:31], v[116:119], v[156:159], v[28:31]
	v_mfma_f32_16x16x32_bf16 v[20:23], v[116:119], v[160:163], v[20:23]
	v_mfma_f32_16x16x32_bf16 v[16:19], v[116:119], v[84:87], v[16:19]
	v_mfma_f32_16x16x32_bf16 v[12:15], v[116:119], v[88:91], v[12:15]
	v_mfma_f32_16x16x32_bf16 v[8:11], v[116:119], v[92:95], v[8:11]
	v_mfma_f32_16x16x32_bf16 v[4:7], v[116:119], v[172:175], v[4:7]
	v_mfma_f32_16x16x32_bf16 v[0:3], v[116:119], v[176:179], v[0:3]
	s_branch .Lsgu_b_done
.Lsgu_b_k0:
	s_waitcnt vmcnt(8)
	s_waitcnt lgkmcnt(0)
	v_mfma_f32_16x16x32_bf16 v[24:27], v[104:107], v[120:123], v[24:27]
	v_mfma_f32_16x16x32_bf16 v[28:31], v[104:107], v[124:127], v[28:31]
	v_mfma_f32_16x16x32_bf16 v[20:23], v[104:107], v[128:131], v[20:23]
	v_mfma_f32_16x16x32_bf16 v[16:19], v[104:107], v[132:135], v[16:19]
	v_mfma_f32_16x16x32_bf16 v[12:15], v[104:107], v[136:139], v[12:15]
	v_mfma_f32_16x16x32_bf16 v[8:11], v[104:107], v[140:143], v[8:11]
	v_mfma_f32_16x16x32_bf16 v[4:7], v[104:107], v[144:147], v[4:7]
	v_mfma_f32_16x16x32_bf16 v[0:3], v[104:107], v[148:151], v[0:3]
	s_branch .Lsgu_b_done
.Lsgu_b_k1:
	s_waitcnt vmcnt(7)
	s_waitcnt lgkmcnt(0)
	v_mfma_f32_16x16x32_bf16 v[24:27], v[108:111], v[152:155], v[24:27]
	v_mfma_f32_16x16x32_bf16 v[28:31], v[108:111], v[156:159], v[28:31]
	v_mfma_f32_16x16x32_bf16 v[20:23], v[108:111], v[160:163], v[20:23]
	v_mfma_f32_16x16x32_bf16 v[16:19], v[108:111], v[84:87], v[16:19]
	v_mfma_f32_16x16x32_bf16 v[12:15], v[108:111], v[88:91], v[12:15]
	v_mfma_f32_16x16x32_bf16 v[8:11], v[108:111], v[92:95], v[8:11]
	v_mfma_f32_16x16x32_bf16 v[4:7], v[108:111], v[172:175], v[4:7]
	v_mfma_f32_16x16x32_bf16 v[0:3], v[108:111], v[176:179], v[0:3]
	s_branch .Lsgu_b_done
.Lsgu_b_k2:
	s_waitcnt vmcnt(6)
	s_waitcnt lgkmcnt(0)
	v_mfma_f32_16x16x32_bf16 v[24:27], v[112:115], v[120:123], v[24:27]
	v_mfma_f32_16x16x32_bf16 v[28:31], v[112:115], v[124:127], v[28:31]
	v_mfma_f32_16x16x32_bf16 v[20:23], v[112:115], v[128:131], v[20:23]
	v_mfma_f32_16x16x32_bf16 v[16:19], v[112:115], v[132:135], v[16:19]
	v_mfma_f32_16x16x32_bf16 v[12:15], v[112:115], v[136:139], v[12:15]
	v_mfma_f32_16x16x32_bf16 v[8:11], v[112:115], v[140:143], v[8:11]
	v_mfma_f32_16x16x32_bf16 v[4:7], v[112:115], v[144:147], v[4:7]
	v_mfma_f32_16x16x32_bf16 v[0:3], v[112:115], v[148:151], v[0:3]

.LBB0_137:
	global_load_dwordx4 v[104:107], v[32:33], off
	global_load_dwordx4 v[108:111], v[32:33], off offset:64
	global_load_dwordx4 v[112:115], v[32:33], off offset:128
	global_load_dwordx4 v[116:119], v[32:33], off offset:192
	ds_read_b128 v[120:123], v36
	ds_read_b128 v[124:127], v36 offset:4352
	ds_read_b128 v[128:131], v36 offset:8704
	ds_read_b128 v[132:135], v36 offset:13056
	ds_read_b128 v[136:139], v36 offset:17408
	ds_read_b128 v[140:143], v36 offset:21760
	ds_read_b128 v[144:147], v36 offset:26112
	ds_read_b128 v[148:151], v36 offset:30464
	s_cmp_lt_u32 s6, 2
	s_cbranch_scc1 .Lsgu_c_k0
	ds_read_b128 v[152:155], v36 offset:64
	ds_read_b128 v[156:159], v36 offset:4416
	ds_read_b128 v[160:163], v36 offset:8768
	ds_read_b128 v[84:87], v36 offset:13120
	ds_read_b128 v[88:91], v36 offset:17472
	ds_read_b128 v[92:95], v36 offset:21824
	ds_read_b128 v[172:175], v36 offset:26176
	ds_read_b128 v[176:179], v36 offset:30528
	s_waitcnt vmcnt(3)
	s_waitcnt lgkmcnt(8)
	v_mfma_f32_16x16x32_bf16 v[24:27], v[104:107], v[120:123], v[24:27]
	v_mfma_f32_16x16x32_bf16 v[28:31], v[104:107], v[124:127], v[28:31]
	v_mfma_f32_16x16x32_bf16 v[20:23], v[104:107], v[128:131], v[20:23]
	v_mfma_f32_16x16x32_bf16 v[16:19], v[104:107], v[132:135], v[16:19]
	v_mfma_f32_16x16x32_bf16 v[12:15], v[104:107], v[136:139], v[12:15]
	v_mfma_f32_16x16x32_bf16 v[8:11], v[104:107], v[140:143], v[8:11]
	v_mfma_f32_16x16x32_bf16 v[4:7], v[104:107], v[144:147], v[4:7]
	v_mfma_f32_16x16x32_bf16 v[0:3], v[104:107], v[148:151], v[0:3]
	s_cmp_lt_u32 s6, 3
	s_cbranch_scc1 .Lsgu_c_k1
	ds_read_b128 v[120:123], v36 offset:128
	ds_read_b128 v[124:127], v36 offset:4480
	ds_read_b128 v[128:131], v36 offset:8832
	ds_read_b128 v[132:135], v36 offset:13184
	ds_read_b128 v[136:139], v36 offset:17536
	ds_read_b128 v[140:143], v36 offset:21888
	ds_read_b128 v[144:147], v36 offset:26240
	ds_read_b128 v[148:151], v36 offset:30592
	s_waitcnt vmcnt(2)
	s_waitcnt lgkmcnt(8)
	v_mfma_f32_16x16x32_bf16 v[24:27], v[108:111], v[152:155], v[24:27]
	v_mfma_f32_16x16x32_bf16 v[28:31], v[108:111], v[156:159], v[28:31]
	v_mfma_f32_16x16x32_bf16 v[20:23], v[108:111], v[160:163], v[20:23]
	v_mfma_f32_16x16x32_bf16 v[16:19], v[108:111], v[84:87], v[16:19]
	v_mfma_f32_16x16x32_bf16 v[12:15], v[108:111], v[88:91], v[12:15]
	v_mfma_f32_16x16x32_bf16 v[8:11], v[108:111], v[92:95], v[8:11]
	v_mfma_f32_16x16x32_bf16 v[4:7], v[108:111], v[172:175], v[4:7]
	v_mfma_f32_16x16x32_bf16 v[0:3], v[108:111], v[176:179], v[0:3]
	s_cmp_lt_u32 s6, 4
	s_cbranch_scc1 .Lsgu_c_k2
	ds_read_b128 v[152:155], v36 offset:192
	ds_read_b128 v[156:159], v36 offset:4544
	ds_read_b128 v[160:163], v36 offset:8896
	ds_read_b128 v[84:87], v36 offset:13248
	ds_read_b128 v[88:91], v36 offset:17600
	ds_read_b128 v[92:95], v36 offset:21952
	ds_read_b128 v[172:175], v36 offset:26304
	ds_read_b128 v[176:179], v36 offset:30656
	s_waitcnt vmcnt(1)
	s_waitcnt lgkmcnt(8)
	v_mfma_f32_16x16x32_bf16 v[24:27], v[112:115], v[120:123], v[24:27]
	v_mfma_f32_16x16x32_bf16 v[28:31], v[112:115], v[124:127], v[28:31]
	v_mfma_f32_16x16x32_bf16 v[20:23], v[112:115], v[128:131], v[20:23]
	v_mfma_f32_16x16x32_bf16 v[16:19], v[112:115], v[132:135], v[16:19]
	v_mfma_f32_16x16x32_bf16 v[12:15], v[112:115], v[136:139], v[12:15]
	v_mfma_f32_16x16x32_bf16 v[8:11], v[112:115], v[140:143], v[8:11]
	v_mfma_f32_16x16x32_bf16 v[4:7], v[112:115], v[144:147], v[4:7]
	v_mfma_f32_16x16x32_bf16 v[0:3], v[112:115], v[148:151], v[0:3]
	s_waitcnt vmcnt(0)
	s_waitcnt lgkmcnt(0)
	v_mfma_f32_16x16x32_bf16 v[24:27], v[116:119], v[152:155], v[24:27]
	v_mfma_f32_16x16x32_bf16 v[28:31], v[116:119], v[156:159], v[28:31]
	v_mfma_f32_16x16x32_bf16 v[20:23], v[116:119], v[160:163], v[20:23]
	v_mfma_f32_16x16x32_bf16 v[16:19], v[116:119], v[84:87], v[16:19]
	v_mfma_f32_16x16x32_bf16 v[12:15], v[116:119], v[88:91], v[12:15]
	v_mfma_f32_16x16x32_bf16 v[8:11], v[116:119], v[92:95], v[8:11]
	v_mfma_f32_16x16x32_bf16 v[4:7], v[116:119], v[172:175], v[4:7]
	v_mfma_f32_16x16x32_bf16 v[0:3], v[116:119], v[176:179], v[0:3]
	s_branch .Lsgu_c_done

.Lsgu_c_done:
	s_mov_b32 s6, 0

.LBB0_618:
	s_or_b64 exec, exec, s[10:11]
	s_lshl_b64 s[4:5], s[16:17], 10
	s_lshl_b64 s[4:5], s[4:5], 2
	s_add_u32 s4, s8, s4
	s_addc_u32 s5, s9, s5
	v_mov_b32_e32 v77, v193
	v_lshl_add_u64 v[24:25], s[4:5], 0, v[76:77]
	s_mov_b64 s[4:5], 0x6cf8000
	v_lshl_add_u64 v[24:25], v[24:25], 0, s[4:5]
	v_add_u32_e32 v132, s6, v78
	v_mov_b64_e32 v[130:131], s[18:19]
	v_mad_i64_i32 v[128:129], s[10:11], v132, s76, v[130:131]
	v_lshl_add_u64 v[128:129], v[128:129], 0, v[192:193]
	s_mov_b64 s[4:5], 0x18400000
	v_lshl_add_u64 v[128:129], v[128:129], 0, s[4:5]
	global_load_dwordx4 v[124:127], v[128:129], off offset:2048
	s_waitcnt vmcnt(0) lgkmcnt(0)
	s_and_saveexec_b64 s[4:5], vcc
	s_cbranch_execz .LBB0_621
	v_lshlrev_b32_e32 v26, 16, v4
	v_and_b32_e32 v27, 0xffff0000, v4
	v_lshlrev_b32_e32 v28, 16, v5
	v_and_b32_e32 v29, 0xffff0000, v5
	v_lshlrev_b32_e32 v4, 16, v6
	v_and_b32_e32 v5, 0xffff0000, v6
	v_lshlrev_b32_e32 v6, 16, v7
	v_and_b32_e32 v7, 0xffff0000, v7
	v_cmp_gt_i32_e32 vcc, 2, v78
	s_nop 1
	v_cndmask_b32_e32 v7, v7, v15, vcc
	v_cndmask_b32_e32 v6, v6, v14, vcc
	v_cndmask_b32_e32 v5, v5, v13, vcc
	v_cndmask_b32_e32 v4, v4, v12, vcc
	v_cndmask_b32_e32 v11, v29, v11, vcc
	v_cndmask_b32_e32 v10, v28, v10, vcc
	v_cndmask_b32_e32 v9, v27, v9, vcc
	v_cndmask_b32_e32 v8, v26, v8, vcc
	v_cmp_lt_i32_e32 vcc, 7, v78
	ds_write_b128 v96, v[8:11]
	ds_write_b128 v96, v[4:7] offset:16
	s_and_b64 exec, exec, vcc
	s_cbranch_execz .LBB0_621
	v_add_u32_e32 v12, -8, v78
	v_mov_b32_e32 v13, v193
	v_lshlrev_b64 v[12:13], 11, v[12:13]
	v_lshl_add_u64 v[12:13], v[24:25], 0, v[12:13]
	global_store_dwordx4 v[12:13], v[8:11], off
	global_store_dwordx4 v[12:13], v[4:7], off offset:16

.LBB0_624:
	s_or_b64 exec, exec, s[4:5]
	s_movk_i32 s0, 0x200
	v_cmp_gt_i32_e32 vcc, s0, v64
	v_cmp_lt_i32_e64 s[0:1], -1, v78
	s_and_b64 s[20:21], vcc, s[0:1]
	v_mov_b32_e32 v0, 0
	v_add_u32_e32 v93, s6, v78
	v_mov_b32_e32 v1, 0
	v_mov_b32_e32 v2, 0
	v_mov_b32_e32 v3, 0
	s_and_saveexec_b64 s[0:1], s[20:21]
	s_cbranch_execz .LBB0_626
	v_mov_b64_e32 v[0:1], s[18:19]
	v_mad_i64_i32 v[0:1], s[4:5], v93, s76, v[0:1]
	v_lshl_add_u64 v[0:1], v[0:1], 0, v[192:193]
	v_add_co_u32_e32 v0, vcc, 0x18400000, v0
	s_nop 1
	v_addc_co_u32_e32 v1, vcc, 0, v1, vcc
	v_mov_b32_e32 v0, v124
	v_mov_b32_e32 v1, v125
	v_mov_b32_e32 v2, v126
	v_mov_b32_e32 v3, v127

.LBB0_689:
	s_or_b64 exec, exec, s[6:7]
	v_readlane_b32 s8, v251, 9
	s_mov_b64 s[6:7], s[42:43]
	s_waitcnt lgkmcnt(0)
	v_mov_b32_e32 v0, s8
	v_readlane_b32 s8, v251, 10
	s_barrier
	ds_read_b128 v[0:3], v0
	v_mov_b32_e32 v4, s8
	ds_read_b128 v[4:7], v4
	v_readlane_b32 s8, v251, 11
	s_add_u32 s6, s6, s14
	s_waitcnt lgkmcnt(1)
	v_add_f32_e32 v0, 0, v0
	v_mov_b32_e32 v8, s8
	v_readlane_b32 s8, v251, 12
	ds_read_b128 v[8:11], v8
	s_waitcnt lgkmcnt(1)
	v_add_f32_e32 v0, v0, v4
	v_mov_b32_e32 v4, s8
	v_readlane_b32 s8, v251, 13
	ds_read_b128 v[12:15], v4
	v_add_f32_e32 v1, 0, v1
	v_mov_b32_e32 v4, s8
	v_readlane_b32 s8, v251, 14
	ds_read_b128 v[16:19], v4
	s_waitcnt lgkmcnt(2)
	v_add_f32_e32 v0, v0, v8
	v_mov_b32_e32 v4, s8
	v_readlane_b32 s8, v251, 15
	ds_read_b128 v[26:29], v4
	v_add_f32_e32 v1, v1, v5
	v_mov_b32_e32 v4, s8
	v_readlane_b32 s8, v251, 16
	ds_read_b128 v[40:43], v4
	s_waitcnt lgkmcnt(3)
	v_add_f32_e32 v0, v0, v12
	v_mov_b32_e32 v4, s8
	ds_read_b128 v[44:47], v4
	v_add_f32_e32 v1, v1, v9
	s_waitcnt lgkmcnt(3)
	v_add_f32_e32 v0, v0, v16
	v_add_f32_e32 v1, v1, v13
	s_waitcnt lgkmcnt(2)
	v_add_f32_e32 v0, v0, v26
	v_add_f32_e32 v1, v1, v17
	s_waitcnt lgkmcnt(1)
	v_add_f32_e32 v0, v0, v40
	v_add_f32_e32 v1, v1, v27
	s_waitcnt lgkmcnt(0)
	v_add_f32_e32 v0, v0, v44
	v_add_f32_e32 v1, v1, v41
	v_mul_f32_e32 v4, 0x3b000000, v0
	v_add_f32_e32 v1, v1, v45
	v_mul_f32_e32 v4, v4, v4
	s_mov_b32 s8, 0x3b000000
	v_fma_f32 v1, v1, s8, -v4
	v_max_f32_e32 v1, 0, v1
	v_add_f32_e32 v1, 0x358637bd, v1
	v_rsq_f32_e32 v1, v1
	v_fmac_f32_e32 v24, 0xbb000000, v0
	v_add_f32_e32 v2, 0, v2
	v_add_f32_e32 v2, v2, v6
	v_mul_f32_e32 v0, v24, v1
	v_fma_f32 v4, v143, v0, v142
	v_mul_f32_e32 v0, 0xbfb8aa3b, v4
	v_exp_f32_e32 v0, v0
	v_add_f32_e32 v3, 0, v3
	v_add_f32_e32 v2, v2, v10
	v_add_f32_e32 v3, v3, v7
	v_add_f32_e32 v0, 1.0, v0
	v_rcp_f32_e32 v5, v0
	v_add_f32_e32 v2, v2, v14
	v_add_f32_e32 v3, v3, v11
	v_add_f32_e32 v2, v2, v18
	v_add_f32_e32 v3, v3, v15
	v_add_f32_e32 v2, v2, v28
	v_add_f32_e32 v3, v3, v19
	v_add_f32_e32 v2, v2, v42
	v_mul_f32_e32 v4, v4, v5
	v_add_f32_e32 v3, v3, v29
	v_add_f32_e32 v2, v2, v46
	v_cvt_pk_bf16_f32 v21, v4, s0
	v_add_f32_e32 v3, v3, v43
	v_mul_f32_e32 v4, 0x3b000000, v2
	v_add_f32_e32 v3, v3, v47
	v_mul_f32_e32 v4, v4, v4
	v_fma_f32 v3, v3, s8, -v4
	v_max_f32_e32 v3, 0, v3
	v_add_f32_e32 v3, 0x358637bd, v3
	v_rsq_f32_e32 v3, v3
	v_fmac_f32_e32 v30, 0xbb000000, v2
	s_addc_u32 s7, s7, s15
	v_lshl_add_u64 v[0:1], v[64:65], 1, s[6:7]
	v_mul_f32_e32 v2, v30, v3
	s_brev_b32 s6, 40
	v_fma_f32 v30, v143, v2, v142
	v_add_co_u32_e32 v18, vcc, s6, v0
	v_mov_b32_e32 v2, s30
	v_mul_f32_e32 v6, 0xbfb8aa3b, v30
	v_readlane_b32 s6, v251, 17
	ds_read_b128 v[2:5], v2
	v_exp_f32_e32 v31, v6
	v_mov_b32_e32 v6, s6
	ds_read_b128 v[6:9], v6
	v_readlane_b32 s6, v251, 18
	s_waitcnt lgkmcnt(1)
	v_add_f32_e32 v2, 0, v2
	v_add_f32_e32 v3, 0, v3
	v_mov_b32_e32 v10, s6
	v_readlane_b32 s6, v251, 19
	ds_read_b128 v[10:13], v10
	s_waitcnt lgkmcnt(1)
	v_add_f32_e32 v2, v2, v6
	v_mov_b32_e32 v6, s6
	v_readlane_b32 s6, v251, 20
	ds_read_b128 v[14:17], v6
	s_waitcnt lgkmcnt(1)
	v_add_f32_e32 v2, v2, v10
	v_mov_b32_e32 v6, s6
	v_readlane_b32 s6, v251, 21
	ds_read_b128 v[22:25], v6
	v_add_f32_e32 v3, v3, v7
	v_mov_b32_e32 v6, s6
	v_readlane_b32 s6, v251, 22
	ds_read_b128 v[26:29], v6
	s_waitcnt lgkmcnt(2)
	v_add_f32_e32 v2, v2, v14
	v_mov_b32_e32 v6, s6
	v_readlane_b32 s6, v251, 23
	ds_read_b128 v[40:43], v6
	v_add_f32_e32 v3, v3, v11
	v_mov_b32_e32 v6, s6
	ds_read_b128 v[44:47], v6
	s_waitcnt lgkmcnt(3)
	v_add_f32_e32 v2, v2, v22
	v_add_f32_e32 v3, v3, v15
	s_waitcnt lgkmcnt(2)
	v_add_f32_e32 v2, v2, v26
	v_add_f32_e32 v3, v3, v23
	s_waitcnt lgkmcnt(1)
	v_add_f32_e32 v2, v2, v40
	v_add_f32_e32 v3, v3, v27
	s_waitcnt lgkmcnt(0)
	v_add_f32_e32 v2, v2, v44
	v_add_f32_e32 v3, v3, v41
	v_mul_f32_e32 v6, 0x3b000000, v2
	v_add_f32_e32 v3, v3, v45
	v_mul_f32_e32 v6, v6, v6
	v_fma_f32 v3, v3, s8, -v6
	v_max_f32_e32 v3, 0, v3
	v_add_f32_e32 v3, 0x358637bd, v3
	v_rsq_f32_e32 v3, v3
	v_fmac_f32_e32 v32, 0xbb000000, v2
	v_add_f32_e32 v6, 1.0, v31
	v_rcp_f32_e32 v6, v6
	v_mul_f32_e32 v2, v32, v3
	v_fma_f32 v7, v143, v2, v142
	v_mul_f32_e32 v2, 0xbfb8aa3b, v7
	v_exp_f32_e32 v2, v2
	v_addc_co_u32_e32 v19, vcc, 0, v1, vcc
	s_mov_b32 s6, 0x14001000
	v_add_f32_e32 v2, 1.0, v2
	v_rcp_f32_e32 v10, v2
	v_mul_f32_e32 v3, v30, v6
	v_add_co_u32_e32 v2, vcc, s6, v0
	v_cvt_pk_bf16_f32 v6, v3, s0
	s_nop 0
	v_addc_co_u32_e32 v3, vcc, 0, v1, vcc
	global_store_short v[2:3], v6, off offset:3072
	v_mul_f32_e32 v2, v7, v10
	v_cvt_pk_bf16_f32 v6, v2, s0
	v_add_f32_e32 v2, 0, v4
	v_add_f32_e32 v3, 0, v5
	v_add_f32_e32 v2, v2, v8
	v_add_f32_e32 v3, v3, v9
	v_add_f32_e32 v2, v2, v12
	v_add_f32_e32 v3, v3, v13
	v_add_f32_e32 v2, v2, v16
	v_add_f32_e32 v3, v3, v17
	v_add_f32_e32 v2, v2, v24
	v_add_f32_e32 v3, v3, v25
	v_add_f32_e32 v2, v2, v28
	v_add_f32_e32 v3, v3, v29
	v_add_f32_e32 v2, v2, v42
	v_add_f32_e32 v3, v3, v43
	v_add_f32_e32 v4, v2, v46
	v_add_f32_e32 v2, v3, v47
	v_mul_f32_e32 v3, 0x3b000000, v4
	v_mul_f32_e32 v3, v3, v3
	v_fma_f32 v2, v2, s8, -v3
	v_max_f32_e32 v2, 0, v2
	v_add_f32_e32 v2, 0x358637bd, v2
	v_rsq_f32_e32 v5, v2
	v_fmac_f32_e32 v34, 0xbb000000, v4
	global_store_short v[18:19], v21, off offset:3072
	s_mov_b32 s6, 0x14002000
	v_mul_f32_e32 v4, v34, v5
	v_fma_f32 v18, v143, v4, v142
	v_mul_f32_e32 v4, 0xbfb8aa3b, v18
	v_exp_f32_e32 v7, v4
	v_add_co_u32_e32 v2, vcc, s6, v0
	v_readlane_b32 s6, v251, 24
	s_nop 0
	v_addc_co_u32_e32 v3, vcc, 0, v1, vcc
	global_store_short v[2:3], v6, off offset:3072
	v_mov_b32_e32 v2, s29
	v_add_f32_e32 v6, 1.0, v7
	ds_read_b128 v[2:5], v2
	v_rcp_f32_e32 v19, v6
	v_mov_b32_e32 v6, s6
	ds_read_b128 v[6:9], v6
	v_readlane_b32 s6, v251, 25
	s_waitcnt lgkmcnt(0)
	v_add_f32_e32 v2, 0, v2
	v_add_f32_e32 v3, 0, v3
	v_mov_b32_e32 v10, s6
	v_readlane_b32 s6, v251, 26
	ds_read_b128 v[10:13], v10
	v_add_f32_e32 v2, v2, v6
	v_mov_b32_e32 v6, s6
	v_readlane_b32 s6, v251, 27
	ds_read_b128 v[14:17], v6
	s_waitcnt lgkmcnt(0)
	v_add_f32_e32 v2, v2, v10
	v_mov_b32_e32 v6, s6
	v_readlane_b32 s6, v251, 28
	ds_read_b128 v[22:25], v6
	v_add_f32_e32 v3, v3, v7
	v_mov_b32_e32 v6, s6
	v_readlane_b32 s6, v251, 29
	ds_read_b128 v[26:29], v6
	v_add_f32_e32 v2, v2, v14
	v_mov_b32_e32 v6, s6
	v_readlane_b32 s6, v251, 30
	ds_read_b128 v[30:33], v6
	v_add_f32_e32 v3, v3, v11
	v_mov_b32_e32 v6, s6
	ds_read_b128 v[40:43], v6
	s_waitcnt lgkmcnt(0)
	v_add_f32_e32 v2, v2, v22
	v_add_f32_e32 v3, v3, v15
	v_add_f32_e32 v2, v2, v26
	v_add_f32_e32 v3, v3, v23
	v_add_f32_e32 v2, v2, v30
	v_add_f32_e32 v3, v3, v27
	v_add_f32_e32 v2, v2, v40
	v_add_f32_e32 v3, v3, v31
	v_mul_f32_e32 v6, 0x3b000000, v2
	v_add_f32_e32 v3, v3, v41
	v_mul_f32_e32 v6, v6, v6
	v_fma_f32 v3, v3, s8, -v6
	v_max_f32_e32 v3, 0, v3
	v_add_f32_e32 v3, 0x358637bd, v3
	v_rsq_f32_e32 v3, v3
	v_fmac_f32_e32 v36, 0xbb000000, v2
	s_mov_b32 s6, 0x14003000
	v_mul_f32_e32 v6, v18, v19
	v_mul_f32_e32 v2, v36, v3
	v_fma_f32 v7, v143, v2, v142
	v_mul_f32_e32 v2, 0xbfb8aa3b, v7
	v_exp_f32_e32 v10, v2
	v_add_co_u32_e32 v2, vcc, s6, v0
	v_cvt_pk_bf16_f32 v6, v6, s0
	s_nop 0
	v_addc_co_u32_e32 v3, vcc, 0, v1, vcc
	global_store_short v[2:3], v6, off offset:3072
	v_add_f32_e32 v3, 0, v4
	v_add_f32_e32 v3, v3, v8
	v_add_f32_e32 v4, 0, v5
	v_add_f32_e32 v3, v3, v12
	v_add_f32_e32 v4, v4, v9
	v_add_f32_e32 v3, v3, v16
	v_add_f32_e32 v4, v4, v13
	v_add_f32_e32 v3, v3, v24
	v_add_f32_e32 v4, v4, v17
	v_add_f32_e32 v3, v3, v28
	v_add_f32_e32 v4, v4, v25
	v_add_f32_e32 v3, v3, v32
	v_add_f32_e32 v4, v4, v29
	v_add_f32_e32 v3, v3, v42
	v_add_f32_e32 v4, v4, v33
	v_mul_f32_e32 v5, 0x3b000000, v3
	v_add_f32_e32 v4, v4, v43
	v_mul_f32_e32 v5, v5, v5
	v_fma_f32 v4, v4, s8, -v5
	v_add_f32_e32 v2, 1.0, v10
	v_max_f32_e32 v4, 0, v4
	v_rcp_f32_e32 v2, v2
	v_add_f32_e32 v4, 0x358637bd, v4
	v_rsq_f32_e32 v4, v4
	v_fmac_f32_e32 v20, 0xbb000000, v3
	v_mul_f32_e32 v2, v7, v2
	v_cvt_pk_bf16_f32 v5, v2, s0
	v_mul_f32_e32 v2, v20, v4
	v_fma_f32 v6, v143, v2, v142
	v_mul_f32_e32 v2, 0xbfb8aa3b, v6
	v_exp_f32_e32 v4, v2
	s_mov_b32 s6, 0x14004000
	v_add_co_u32_e32 v2, vcc, s6, v0
	v_add_f32_e32 v4, 1.0, v4
	v_rcp_f32_e32 v7, v4
	v_addc_co_u32_e32 v3, vcc, 0, v1, vcc
	global_store_short v[2:3], v5, off offset:3072
	v_mov_b32_e32 v2, s28
	v_mul_f32_e32 v6, v6, v7
	v_readlane_b32 s6, v251, 31
	ds_read_b128 v[2:5], v2
	v_cvt_pk_bf16_f32 v34, v6, s0
	v_mov_b32_e32 v6, s6
	ds_read_b128 v[6:9], v6
	v_readlane_b32 s6, v251, 32
	s_waitcnt lgkmcnt(0)
	v_add_f32_e32 v2, 0, v2
	v_add_f32_e32 v3, 0, v3
	v_mov_b32_e32 v10, s6
	v_readlane_b32 s6, v251, 33
	ds_read_b128 v[10:13], v10
	v_add_f32_e32 v2, v2, v6
	v_mov_b32_e32 v6, s6
	v_readlane_b32 s6, v251, 34
	ds_read_b128 v[14:17], v6
	v_add_f32_e32 v3, v3, v7
	v_mov_b32_e32 v6, s6
	v_readlane_b32 s6, v251, 35
	ds_read_b128 v[18:21], v6
	s_waitcnt lgkmcnt(0)
	v_add_f32_e32 v2, v2, v10
	v_mov_b32_e32 v6, s6
	v_readlane_b32 s6, v251, 36
	ds_read_b128 v[22:25], v6
	v_add_f32_e32 v3, v3, v11
	v_mov_b32_e32 v6, s6
	v_readlane_b32 s6, v251, 37
	ds_read_b128 v[26:29], v6
	v_add_f32_e32 v2, v2, v14
	v_mov_b32_e32 v6, s6
	ds_read_b128 v[30:33], v6
	v_add_f32_e32 v3, v3, v15
	v_add_f32_e32 v2, v2, v18
	v_add_f32_e32 v3, v3, v19
	s_waitcnt lgkmcnt(0)
	v_add_f32_e32 v2, v2, v22
	v_add_f32_e32 v3, v3, v23
	v_add_f32_e32 v2, v2, v26
	v_add_f32_e32 v4, 0, v4
	v_add_f32_e32 v3, v3, v27
	v_add_f32_e32 v6, v2, v30
	v_add_f32_e32 v4, v4, v8
	v_add_f32_e32 v2, v3, v31
	v_mul_f32_e32 v3, 0x3b000000, v6
	v_add_f32_e32 v5, 0, v5
	v_add_f32_e32 v4, v4, v12
	v_mul_f32_e32 v3, v3, v3
	v_add_f32_e32 v5, v5, v9
	v_add_f32_e32 v4, v4, v16
	v_fma_f32 v2, v2, s8, -v3
	v_add_f32_e32 v5, v5, v13
	v_add_f32_e32 v4, v4, v20
	v_max_f32_e32 v2, 0, v2
	v_add_f32_e32 v5, v5, v17
	v_add_f32_e32 v4, v4, v24
	v_add_f32_e32 v2, 0x358637bd, v2
	v_add_f32_e32 v5, v5, v21
	v_add_f32_e32 v4, v4, v28
	v_rsq_f32_e32 v7, v2
	v_add_f32_e32 v5, v5, v25
	v_add_f32_e32 v4, v4, v32
	v_add_f32_e32 v5, v5, v29
	v_mul_f32_e32 v8, 0x3b000000, v4
	v_add_f32_e32 v5, v5, v33
	v_mul_f32_e32 v8, v8, v8
	v_fmac_f32_e32 v38, 0xbb000000, v6
	v_fma_f32 v5, v5, s8, -v8
	v_mul_f32_e32 v6, v38, v7
	v_max_f32_e32 v5, 0, v5
	v_fma_f32 v6, v143, v6, v142
	v_add_f32_e32 v5, 0x358637bd, v5
	v_mul_f32_e32 v7, 0xbfb8aa3b, v6
	v_rsq_f32_e32 v5, v5
	v_exp_f32_e32 v7, v7
	v_fmac_f32_e32 v60, 0xbb000000, v4
	s_mov_b32 s6, 0x14005000
	v_mul_f32_e32 v4, v60, v5
	v_add_f32_e32 v7, 1.0, v7
	v_fmac_f32_e32 v142, v143, v4
	v_rcp_f32_e32 v7, v7
	v_mul_f32_e32 v4, 0xbfb8aa3b, v142
	v_exp_f32_e32 v4, v4
	v_add_co_u32_e32 v2, vcc, s6, v0
	s_mov_b32 s6, 0x14006000
	s_nop 0
	v_addc_co_u32_e32 v3, vcc, 0, v1, vcc
	global_store_short v[2:3], v34, off offset:3072
	v_mul_f32_e32 v2, v6, v7
	v_cvt_pk_bf16_f32 v5, v2, s0
	v_add_f32_e32 v2, 1.0, v4
	v_rcp_f32_e32 v4, v2
	v_add_co_u32_e32 v2, vcc, s6, v0
	s_nop 1
	v_addc_co_u32_e32 v3, vcc, 0, v1, vcc
	global_store_short v[2:3], v5, off offset:3072
	v_mul_f32_e32 v2, v142, v4
	v_add_co_u32_e32 v0, vcc, 0x14007000, v0
	v_cvt_pk_bf16_f32 v2, v2, s0
	s_nop 0
	v_addc_co_u32_e32 v1, vcc, 0, v1, vcc
	global_store_short v[0:1], v2, off offset:3072
	v_mov_b32_e32 v0, 0
	v_mov_b32_e32 v1, 0
	v_mov_b32_e32 v2, 0
	v_mov_b32_e32 v3, 0
	s_waitcnt lgkmcnt(0)
	s_barrier
	s_and_saveexec_b64 s[6:7], s[20:21]
	s_cbranch_execz .LBB0_691
	v_mov_b64_e32 v[0:1], s[18:19]
	v_mad_i64_i32 v[0:1], s[8:9], v93, s76, v[0:1]
	v_lshl_add_u64 v[0:1], v[0:1], 0, v[192:193]
	v_add_co_u32_e32 v0, vcc, 0x18401000, v0
	s_nop 1
	v_addc_co_u32_e32 v1, vcc, 0, v1, vcc
	global_load_dwordx4 v[0:3], v[0:1], off
	v_mov_b64_e32 v[128:129], s[18:19]
	v_mad_i64_i32 v[128:129], s[8:9], v93, s76, v[128:129]
	v_lshl_add_u64 v[128:129], v[128:129], 0, v[192:193]
	v_add_co_u32_e32 v128, vcc, 0x18400000, v128
	s_nop 1
	v_addc_co_u32_e32 v129, vcc, 0, v129, vcc
	global_load_dwordx4 v[124:127], v[128:129], off offset:3072

.LBB0_693:
	s_or_b64 exec, exec, s[6:7]
	s_waitcnt vmcnt(0) lgkmcnt(0)
	v_mov_b32_e32 v0, 0
	v_mov_b32_e32 v1, 0
	v_mov_b32_e32 v2, 0
	v_mov_b32_e32 v3, 0
	s_and_saveexec_b64 s[6:7], s[20:21]
	s_cbranch_execz .LBB0_695
	v_mov_b64_e32 v[0:1], s[18:19]
	v_mad_i64_i32 v[0:1], s[8:9], v93, s76, v[0:1]
	v_lshl_add_u64 v[0:1], v[0:1], 0, v[192:193]
	v_add_co_u32_e32 v0, vcc, 0x18400000, v0
	s_nop 1
	v_addc_co_u32_e32 v1, vcc, 0, v1, vcc
	v_mov_b32_e32 v0, v124
	v_mov_b32_e32 v1, v125
	v_mov_b32_e32 v2, v126
	v_mov_b32_e32 v3, v127
